# group barrier fast path: one returning atomic on a single counter, early L1 invalidate, poll only if not last
# baseline (speedup 1.0000x reference)
; __device__ __forceinline__ unsigned xb_ld(unsigned* p)              { return __hip_atomic_load(p, __ATOMIC_RELAXED, __HIP_MEMORY_SCOPE_AGENT); }
; __device__ __forceinline__ unsigned xb_add(unsigned* p, unsigned v) { return __hip_atomic_fetch_add(p, v, __ATOMIC_RELAXED, __HIP_MEMORY_SCOPE_AGENT); }
; #define XB_SPIN(cond, bar) do { unsigned _sp = 0; while (cond) { __builtin_amdgcn_s_sleep(1); \
;     if ((++_sp & 255u) == 0u) { if (xb_ld(&(bar)[XB_TMO])) break; if (_sp > XB_SPIN_CAP) { atomicAdd(&(bar)[XB_TMO], 1u); break; } } } } while (0)
; __device__ __forceinline__ void xcd_barrier(const XcdBarrier& b) {
;     asm volatile("s_waitcnt vmcnt(0)" ::: "memory");
;     __syncthreads();
;     if (threadIdx.x == 0) {
;         unsigned* bar = b.bar;
;         __builtin_amdgcn_s_waitcnt(0);
;         unsigned nloc = b.st[0], nx = b.st[1];
;         if (nloc == 0u) { xcd_barrier_complete(bar, b.x, b.gsz, nloc, nx); b.st[0] = nloc; b.st[1] = nx; }
;         const unsigned old = xb_add(&bar[XB_XSUB(b.x)], 1u);
;         const unsigned gen = old / nloc;
;         if (old + 1u == (gen + 1u) * nloc) {
;             __builtin_amdgcn_fence(__ATOMIC_RELEASE, "agent");
;             asm volatile("s_waitcnt vmcnt(0)" ::: "memory");
;             const unsigned og = xb_add(&bar[XB_TOP], 1u);
;             const unsigned tg = og / nx;
;             if (og + 1u == (tg + 1u) * nx) xb_add(&bar[XB_TOPGEN], 1u);
;             else XB_SPIN(xb_ld(&bar[XB_TOPGEN]) == tg, bar);
;             __builtin_amdgcn_fence(__ATOMIC_ACQUIRE, "agent");
;             xb_add(&bar[XB_XGEN(b.x)], 1u);
;             asm volatile("s_waitcnt vmcnt(0)" ::: "memory");
;         } else {
;             XB_SPIN(xb_ld(&bar[XB_XGEN(b.x)]) == gen, bar);
;             __builtin_amdgcn_fence(__ATOMIC_ACQUIRE, "agent");
;             asm volatile("s_waitcnt vmcnt(0)" ::: "memory");
;         }
;     }
;     __syncthreads();
; }
.LBB0_199:
	s_waitcnt lgkmcnt(0)
	v_cmp_ne_u32_e32 vcc, 1, v0
	s_cbranch_vccnz .Lxslow_1
	s_lshl_b32 s4, s33, 8
	s_add_u32 s4, s54, s4
	s_addc_u32 s5, s55, 0
	s_add_i32 s100, s100, 1
	v_mov_b32_e32 v1, 0x1000
	v_mov_b32_e32 v3, 1
	global_atomic_add v0, v1, v3, s[4:5] offset:1024 sc0
	v_mul_lo_u32 v2, v2, s100
	s_mov_b32 s101, 0
	s_waitcnt vmcnt(0)
	buffer_inv sc1
	v_add_u32_e32 v0, 1, v0
.Lxspin_1:
	v_sub_u32_e32 v0, v0, v2
	v_cmp_gt_i32_e32 vcc, 0, v0
	s_cbranch_vccz .Lxdone_1
	s_add_i32 s101, s101, 1
	s_cmp_gt_u32 s101, 0x8000
	s_cbranch_scc1 .Lxdone_1
	s_sleep 1
	global_load_dword v0, v1, s[4:5] offset:1024 sc1
	s_waitcnt vmcnt(0)
	s_branch .Lxspin_1
.Lxdone_1:
	s_waitcnt vmcnt(0)
	s_branch .LBB0_228

; __device__ __forceinline__ unsigned xb_ld(unsigned* p)              { return __hip_atomic_load(p, __ATOMIC_RELAXED, __HIP_MEMORY_SCOPE_AGENT); }
; __device__ __forceinline__ unsigned xb_add(unsigned* p, unsigned v) { return __hip_atomic_fetch_add(p, v, __ATOMIC_RELAXED, __HIP_MEMORY_SCOPE_AGENT); }
; #define XB_SPIN(cond, bar) do { unsigned _sp = 0; while (cond) { __builtin_amdgcn_s_sleep(1); \
;     if ((++_sp & 255u) == 0u) { if (xb_ld(&(bar)[XB_TMO])) break; if (_sp > XB_SPIN_CAP) { atomicAdd(&(bar)[XB_TMO], 1u); break; } } } } while (0)
; __device__ __forceinline__ void xcd_barrier(const XcdBarrier& b) {
;     ...
;     if (threadIdx.x == 0) {
;         unsigned* bar = b.bar;
;         __builtin_amdgcn_s_waitcnt(0);
;         unsigned nloc = b.st[0], nx = b.st[1];
;         if (nloc == 0u) { xcd_barrier_complete(bar, b.x, b.gsz, nloc, nx); b.st[0] = nloc; b.st[1] = nx; }
;         const unsigned old = xb_add(&bar[XB_XSUB(b.x)], 1u);
;         const unsigned gen = old / nloc;
;         if (old + 1u == (gen + 1u) * nloc) {
;             __builtin_amdgcn_fence(__ATOMIC_RELEASE, "agent");
;             asm volatile("s_waitcnt vmcnt(0)" ::: "memory");
;             const unsigned og = xb_add(&bar[XB_TOP], 1u);
;             const unsigned tg = og / nx;
;             if (og + 1u == (tg + 1u) * nx) xb_add(&bar[XB_TOPGEN], 1u);
;             else XB_SPIN(xb_ld(&bar[XB_TOPGEN]) == tg, bar);
;             __builtin_amdgcn_fence(__ATOMIC_ACQUIRE, "agent");
;             xb_add(&bar[XB_XGEN(b.x)], 1u);
;             asm volatile("s_waitcnt vmcnt(0)" ::: "memory");
;         } else {
;             XB_SPIN(xb_ld(&bar[XB_XGEN(b.x)]) == gen, bar);
;             __builtin_amdgcn_fence(__ATOMIC_ACQUIRE, "agent");
;             asm volatile("s_waitcnt vmcnt(0)" ::: "memory");
;         }
.LBB0_490:
	s_waitcnt lgkmcnt(0)
	v_cmp_ne_u32_e32 vcc, 1, v0
	s_cbranch_vccnz .Lxslow_5
	s_lshl_b32 s2, s33, 8
	s_add_u32 s4, s54, s2
	s_addc_u32 s5, s55, 0
	s_add_i32 s100, s100, 1
	v_mov_b32_e32 v1, 0x1000
	v_mov_b32_e32 v3, 1
	global_atomic_add v0, v1, v3, s[4:5] offset:1024 sc0
	v_mul_lo_u32 v2, v2, s100
	s_mov_b32 s101, 0
	s_waitcnt vmcnt(0)
	buffer_inv sc1
	v_add_u32_e32 v0, 1, v0

; __device__ __forceinline__ unsigned xb_ld(unsigned* p)              { return __hip_atomic_load(p, __ATOMIC_RELAXED, __HIP_MEMORY_SCOPE_AGENT); }
; __device__ __forceinline__ unsigned xb_add(unsigned* p, unsigned v) { return __hip_atomic_fetch_add(p, v, __ATOMIC_RELAXED, __HIP_MEMORY_SCOPE_AGENT); }
; #define XB_SPIN(cond, bar) do { unsigned _sp = 0; while (cond) { __builtin_amdgcn_s_sleep(1); \
;     if ((++_sp & 255u) == 0u) { if (xb_ld(&(bar)[XB_TMO])) break; if (_sp > XB_SPIN_CAP) { atomicAdd(&(bar)[XB_TMO], 1u); break; } } } } while (0)
; __device__ __forceinline__ void xcd_barrier(const XcdBarrier& b) {
;     ...
;     if (threadIdx.x == 0) {
;         unsigned* bar = b.bar;
;         __builtin_amdgcn_s_waitcnt(0);
;         unsigned nloc = b.st[0], nx = b.st[1];
;         if (nloc == 0u) { xcd_barrier_complete(bar, b.x, b.gsz, nloc, nx); b.st[0] = nloc; b.st[1] = nx; }
;         const unsigned old = xb_add(&bar[XB_XSUB(b.x)], 1u);
;         const unsigned gen = old / nloc;
;         if (old + 1u == (gen + 1u) * nloc) {
;             __builtin_amdgcn_fence(__ATOMIC_RELEASE, "agent");
;             asm volatile("s_waitcnt vmcnt(0)" ::: "memory");
;             const unsigned og = xb_add(&bar[XB_TOP], 1u);
;             const unsigned tg = og / nx;
;             if (og + 1u == (tg + 1u) * nx) xb_add(&bar[XB_TOPGEN], 1u);
;             else XB_SPIN(xb_ld(&bar[XB_TOPGEN]) == tg, bar);
;             __builtin_amdgcn_fence(__ATOMIC_ACQUIRE, "agent");
;             xb_add(&bar[XB_XGEN(b.x)], 1u);
;             asm volatile("s_waitcnt vmcnt(0)" ::: "memory");
;         } else {
;             XB_SPIN(xb_ld(&bar[XB_XGEN(b.x)]) == gen, bar);
;             __builtin_amdgcn_fence(__ATOMIC_ACQUIRE, "agent");
;             asm volatile("s_waitcnt vmcnt(0)" ::: "memory");
;         }
.LBB0_540:
	s_waitcnt lgkmcnt(0)
	v_cmp_ne_u32_e32 vcc, 1, v0
	s_cbranch_vccnz .Lxslow_6
	s_lshl_b32 s2, s33, 8
	s_add_u32 s6, s54, s2
	s_addc_u32 s7, s55, 0
	s_add_i32 s100, s100, 1
	v_mov_b32_e32 v1, 0x1000
	v_mov_b32_e32 v3, 1
	global_atomic_add v0, v1, v3, s[6:7] offset:1024 sc0
	v_mul_lo_u32 v2, v2, s100
	s_mov_b32 s101, 0
	s_waitcnt vmcnt(0)
	buffer_inv sc1
	v_add_u32_e32 v0, 1, v0
.Lxspin_6:
	v_sub_u32_e32 v0, v0, v2
	v_cmp_gt_i32_e32 vcc, 0, v0
	s_cbranch_vccz .Lxdone_6
	s_add_i32 s101, s101, 1
	s_cmp_gt_u32 s101, 0x8000
	s_cbranch_scc1 .Lxdone_6
	s_sleep 1
	global_load_dword v0, v1, s[6:7] offset:1024 sc1
	s_waitcnt vmcnt(0)
	s_branch .Lxspin_6
